# v22 + removed the per-XCD XGEN atomic add from the leaders' exit path (no WG reads XGEN any more, so leaders no longer wait for its ack)
# baseline (speedup 1.0000x reference)
; __device__ __forceinline__ unsigned xb_add(unsigned* p, unsigned v) { return __hip_atomic_fetch_add(p, v, __ATOMIC_RELAXED, __HIP_MEMORY_SCOPE_AGENT); }
; __device__ __forceinline__ void xcd_barrier(const XcdBarrier& b, const int wid) {
;     ...
;             __builtin_amdgcn_fence(__ATOMIC_ACQUIRE, "agent");
;             xb_add(&bar[XB_XGEN(b.x)], 1u);
;             asm volatile("s_waitcnt vmcnt(0)" ::: "memory");
.LBB0_358:
	s_or_b64 exec, exec, s[10:11]
	s_mov_b64 s[10:11], exec
	v_mbcnt_lo_u32_b32 v0, s10, 0
	v_mbcnt_hi_u32_b32 v0, s11, v0
	v_cmp_eq_u32_e32 vcc, 0, v0
	s_waitcnt vmcnt(0)
	buffer_inv sc1
	s_and_saveexec_b64 s[12:13], vcc
	s_cbranch_execz .LBB0_360
	s_bcnt1_i32_b64 s3, s[10:11]
	v_mov_b32_e32 v0, 0x2000
	v_mov_b32_e32 v1, s3
.LBB0_360:
	s_or_b64 exec, exec, s[12:13]
	s_waitcnt vmcnt(0)

; __device__ __forceinline__ unsigned xb_add(unsigned* p, unsigned v) { return __hip_atomic_fetch_add(p, v, __ATOMIC_RELAXED, __HIP_MEMORY_SCOPE_AGENT); }
; __device__ __forceinline__ void xcd_barrier(const XcdBarrier& b, const int wid) {
;     ...
;             __builtin_amdgcn_fence(__ATOMIC_ACQUIRE, "agent");
;             xb_add(&bar[XB_XGEN(b.x)], 1u);
;             asm volatile("s_waitcnt vmcnt(0)" ::: "memory");
.LBB0_472:
	s_or_b64 exec, exec, s[10:11]
	s_mov_b64 s[10:11], exec
	v_mbcnt_lo_u32_b32 v0, s10, 0
	v_mbcnt_hi_u32_b32 v0, s11, v0
	v_cmp_eq_u32_e32 vcc, 0, v0
	s_waitcnt vmcnt(0)
	buffer_inv sc1
	s_and_saveexec_b64 s[12:13], vcc
	s_cbranch_execz .LBB0_474
	s_bcnt1_i32_b64 s3, s[10:11]
	v_mov_b32_e32 v0, 0x2000
	v_mov_b32_e32 v1, s3
.LBB0_474:
	s_or_b64 exec, exec, s[12:13]
	s_waitcnt vmcnt(0)

; __device__ __forceinline__ unsigned xb_add(unsigned* p, unsigned v) { return __hip_atomic_fetch_add(p, v, __ATOMIC_RELAXED, __HIP_MEMORY_SCOPE_AGENT); }
; __device__ __forceinline__ void xcd_barrier(const XcdBarrier& b, const int wid) {
;     ...
;             __builtin_amdgcn_fence(__ATOMIC_ACQUIRE, "agent");
;             xb_add(&bar[XB_XGEN(b.x)], 1u);
;             asm volatile("s_waitcnt vmcnt(0)" ::: "memory");
.LBB0_635:
	s_or_b64 exec, exec, s[10:11]
	s_mov_b64 s[10:11], exec
	v_mbcnt_lo_u32_b32 v0, s10, 0
	v_mbcnt_hi_u32_b32 v0, s11, v0
	v_cmp_eq_u32_e32 vcc, 0, v0
	s_waitcnt vmcnt(0)
	buffer_inv sc1
	s_and_saveexec_b64 s[12:13], vcc
	s_cbranch_execz .LBB0_637
	s_bcnt1_i32_b64 s3, s[10:11]
	v_mov_b32_e32 v0, 0x2000
	v_mov_b32_e32 v1, s3
.LBB0_637:
	s_or_b64 exec, exec, s[12:13]
	s_waitcnt vmcnt(0)

; __device__ __forceinline__ unsigned xb_add(unsigned* p, unsigned v) { return __hip_atomic_fetch_add(p, v, __ATOMIC_RELAXED, __HIP_MEMORY_SCOPE_AGENT); }
; __device__ __forceinline__ void xcd_barrier(const XcdBarrier& b, const int wid) {
;     ...
;             __builtin_amdgcn_fence(__ATOMIC_ACQUIRE, "agent");
;             xb_add(&bar[XB_XGEN(b.x)], 1u);
;             asm volatile("s_waitcnt vmcnt(0)" ::: "memory");
.LBB0_2037:
	s_or_b64 exec, exec, s[10:11]
	s_mov_b64 s[10:11], exec
	v_mbcnt_lo_u32_b32 v0, s10, 0
	v_mbcnt_hi_u32_b32 v0, s11, v0
	v_cmp_eq_u32_e32 vcc, 0, v0
	s_waitcnt vmcnt(0)
	buffer_inv sc1
	s_and_saveexec_b64 s[12:13], vcc
	s_cbranch_execz .LBB0_2039
	s_bcnt1_i32_b64 s3, s[10:11]
	v_mov_b32_e32 v0, 0x2000
	v_mov_b32_e32 v1, s3
.LBB0_2039:
	s_or_b64 exec, exec, s[12:13]
	s_waitcnt vmcnt(0)

; __device__ __forceinline__ unsigned xb_add(unsigned* p, unsigned v) { return __hip_atomic_fetch_add(p, v, __ATOMIC_RELAXED, __HIP_MEMORY_SCOPE_AGENT); }
; __device__ __forceinline__ void xcd_barrier(const XcdBarrier& b, const int wid) {
;     ...
;             __builtin_amdgcn_fence(__ATOMIC_ACQUIRE, "agent");
;             xb_add(&bar[XB_XGEN(b.x)], 1u);
;             asm volatile("s_waitcnt vmcnt(0)" ::: "memory");
.LBB0_2215:
	s_or_b64 exec, exec, s[12:13]
	s_mov_b64 s[12:13], exec
	v_mbcnt_lo_u32_b32 v0, s12, 0
	v_mbcnt_hi_u32_b32 v0, s13, v0
	v_cmp_eq_u32_e32 vcc, 0, v0
	s_waitcnt vmcnt(0)
	buffer_inv sc1
	s_and_saveexec_b64 s[14:15], vcc
	s_cbranch_execz .LBB0_2217
	s_bcnt1_i32_b64 s3, s[12:13]
	v_mov_b32_e32 v0, 0x2000
	v_mov_b32_e32 v1, s3
.LBB0_2217:
	s_or_b64 exec, exec, s[14:15]
	s_waitcnt vmcnt(0)

; __device__ __forceinline__ unsigned xb_add(unsigned* p, unsigned v) { return __hip_atomic_fetch_add(p, v, __ATOMIC_RELAXED, __HIP_MEMORY_SCOPE_AGENT); }
; __device__ __forceinline__ void xcd_barrier(const XcdBarrier& b, const int wid) {
;     ...
;             __builtin_amdgcn_fence(__ATOMIC_ACQUIRE, "agent");
;             xb_add(&bar[XB_XGEN(b.x)], 1u);
;             asm volatile("s_waitcnt vmcnt(0)" ::: "memory");
.LBB0_2274:
	s_or_b64 exec, exec, s[10:11]
	s_mov_b64 s[10:11], exec
	v_mbcnt_lo_u32_b32 v0, s10, 0
	v_mbcnt_hi_u32_b32 v0, s11, v0
	v_cmp_eq_u32_e32 vcc, 0, v0
	s_waitcnt vmcnt(0)
	buffer_inv sc1
	s_and_saveexec_b64 s[12:13], vcc
	s_cbranch_execz .LBB0_2276
	s_bcnt1_i32_b64 s3, s[10:11]
	v_mov_b32_e32 v0, 0x2000
	v_mov_b32_e32 v1, s3
.LBB0_2276:
	s_or_b64 exec, exec, s[12:13]
	s_waitcnt vmcnt(0)

; __device__ __forceinline__ unsigned xb_add(unsigned* p, unsigned v) { return __hip_atomic_fetch_add(p, v, __ATOMIC_RELAXED, __HIP_MEMORY_SCOPE_AGENT); }
; __device__ __forceinline__ void xcd_barrier(const XcdBarrier& b, const int wid) {
;     ...
;             __builtin_amdgcn_fence(__ATOMIC_ACQUIRE, "agent");
;             xb_add(&bar[XB_XGEN(b.x)], 1u);
;             asm volatile("s_waitcnt vmcnt(0)" ::: "memory");
.LBB0_2352:
	s_or_b64 exec, exec, s[10:11]
	s_mov_b64 s[10:11], exec
	v_mbcnt_lo_u32_b32 v0, s10, 0
	v_mbcnt_hi_u32_b32 v0, s11, v0
	v_cmp_eq_u32_e32 vcc, 0, v0
	s_waitcnt vmcnt(0)
	buffer_inv sc1
	s_and_saveexec_b64 s[12:13], vcc
	s_cbranch_execz .LBB0_2354
	s_bcnt1_i32_b64 s3, s[10:11]
	v_mov_b32_e32 v0, 0x2000
	v_mov_b32_e32 v1, s3
.LBB0_2354:
	s_or_b64 exec, exec, s[12:13]
	s_waitcnt vmcnt(0)

; __device__ __forceinline__ unsigned xb_add(unsigned* p, unsigned v) { return __hip_atomic_fetch_add(p, v, __ATOMIC_RELAXED, __HIP_MEMORY_SCOPE_AGENT); }
; __device__ __forceinline__ void xcd_barrier(const XcdBarrier& b, const int wid) {
;     ...
;             __builtin_amdgcn_fence(__ATOMIC_ACQUIRE, "agent");
;             xb_add(&bar[XB_XGEN(b.x)], 1u);
;             asm volatile("s_waitcnt vmcnt(0)" ::: "memory");
.LBB0_2438:
	s_or_b64 exec, exec, s[10:11]
	s_mov_b64 s[10:11], exec
	v_mbcnt_lo_u32_b32 v0, s10, 0
	v_mbcnt_hi_u32_b32 v0, s11, v0
	v_cmp_eq_u32_e32 vcc, 0, v0
	s_waitcnt vmcnt(0)
	buffer_inv sc1
	s_and_saveexec_b64 s[12:13], vcc
	s_cbranch_execz .LBB0_2440
	s_bcnt1_i32_b64 s3, s[10:11]
	v_mov_b32_e32 v0, 0x2000
	v_mov_b32_e32 v1, s3
.LBB0_2440:
	s_or_b64 exec, exec, s[12:13]
	s_waitcnt vmcnt(0)

; __device__ __forceinline__ unsigned xb_add(unsigned* p, unsigned v) { return __hip_atomic_fetch_add(p, v, __ATOMIC_RELAXED, __HIP_MEMORY_SCOPE_AGENT); }
; __device__ __forceinline__ void xcd_barrier(const XcdBarrier& b, const int wid) {
;     ...
;             __builtin_amdgcn_fence(__ATOMIC_ACQUIRE, "agent");
;             xb_add(&bar[XB_XGEN(b.x)], 1u);
;             asm volatile("s_waitcnt vmcnt(0)" ::: "memory");
.LBB0_2511:
	s_or_b64 exec, exec, s[10:11]
	s_mov_b64 s[10:11], exec
	v_mbcnt_lo_u32_b32 v0, s10, 0
	v_mbcnt_hi_u32_b32 v0, s11, v0
	v_cmp_eq_u32_e32 vcc, 0, v0
	s_waitcnt vmcnt(0)
	buffer_inv sc1
	s_and_saveexec_b64 s[12:13], vcc
	s_cbranch_execz .LBB0_2513
	s_bcnt1_i32_b64 s3, s[10:11]
	v_mov_b32_e32 v0, 0x2000
	v_mov_b32_e32 v1, s3
.LBB0_2513:
	s_or_b64 exec, exec, s[12:13]
	s_waitcnt vmcnt(0)

; __device__ __forceinline__ unsigned xb_add(unsigned* p, unsigned v) { return __hip_atomic_fetch_add(p, v, __ATOMIC_RELAXED, __HIP_MEMORY_SCOPE_AGENT); }
; __device__ __forceinline__ void xcd_barrier(const XcdBarrier& b, const int wid) {
;     ...
;             __builtin_amdgcn_fence(__ATOMIC_ACQUIRE, "agent");
;             xb_add(&bar[XB_XGEN(b.x)], 1u);
;             asm volatile("s_waitcnt vmcnt(0)" ::: "memory");
.LBB0_2598:
	s_or_b64 exec, exec, s[8:9]
	s_mov_b64 s[8:9], exec
	v_mbcnt_lo_u32_b32 v0, s8, 0
	v_mbcnt_hi_u32_b32 v0, s9, v0
	v_cmp_eq_u32_e32 vcc, 0, v0
	s_waitcnt vmcnt(0)
	buffer_inv sc1
	s_and_saveexec_b64 s[10:11], vcc
	s_cbranch_execz .LBB0_2600
	s_bcnt1_i32_b64 s8, s[8:9]
	v_mov_b32_e32 v0, 0x2000
	v_mov_b32_e32 v1, s8
.LBB0_2600:
	s_or_b64 exec, exec, s[10:11]
	s_waitcnt vmcnt(0)
